# fused rwkv_scalars in prep, 1/W by v_rcp_f32 of the running decay product instead of a second exp chain
# baseline (speedup 1.0000x reference)
.Lrwq_noq0_a:
	s_add_u32 s0, s0, 0x5200
	s_addc_u32 s1, s1, 0
	global_load_short_d16_hi v100, v175, s[0:1] offset:-2048
	global_load_short_d16_hi v108, v175, s[0:1]
	global_load_short_d16_hi v116, v175, s[0:1] offset:2048
	s_add_u32 s0, s0, 0x5200
	s_addc_u32 s1, s1, 0
	global_load_short_d16_hi v101, v175, s[0:1] offset:-2048
	global_load_short_d16_hi v109, v175, s[0:1]
	global_load_short_d16_hi v117, v175, s[0:1] offset:2048
	s_add_u32 s0, s0, 0x5200
	s_addc_u32 s1, s1, 0
	global_load_short_d16_hi v102, v175, s[0:1] offset:-2048
	global_load_short_d16_hi v110, v175, s[0:1]
	global_load_short_d16_hi v118, v175, s[0:1] offset:2048
	s_add_u32 s0, s0, 0x5200
	s_addc_u32 s1, s1, 0
	global_load_short_d16_hi v103, v175, s[0:1] offset:-2048
	global_load_short_d16_hi v111, v175, s[0:1]
	global_load_short_d16_hi v119, v175, s[0:1] offset:2048
	s_add_u32 s0, s0, 0x5200
	s_addc_u32 s1, s1, 0
	global_load_short_d16_hi v104, v175, s[0:1] offset:-2048
	global_load_short_d16_hi v112, v175, s[0:1]
	global_load_short_d16_hi v120, v175, s[0:1] offset:2048
	s_add_u32 s0, s0, 0x5200
	s_addc_u32 s1, s1, 0
	global_load_short_d16_hi v105, v175, s[0:1] offset:-2048
	global_load_short_d16_hi v113, v175, s[0:1]
	global_load_short_d16_hi v121, v175, s[0:1] offset:2048
	s_add_u32 s0, s0, 0x5200
	s_addc_u32 s1, s1, 0
	global_load_short_d16_hi v106, v175, s[0:1] offset:-2048
	global_load_short_d16_hi v114, v175, s[0:1]
	global_load_short_d16_hi v122, v175, s[0:1] offset:2048
	s_add_u32 s0, s0, 0x5200
	s_addc_u32 s1, s1, 0
	global_load_short_d16_hi v107, v175, s[0:1] offset:-2048
	global_load_short_d16_hi v115, v175, s[0:1]
	global_load_short_d16_hi v123, v175, s[0:1] offset:2048
	s_add_u32 s0, s100, 0x0
	s_addc_u32 s1, s101, 0
	global_load_short_d16_hi v124, v175, s[0:1]
	global_load_short_d16_hi v125, v175, s[0:1] offset:2048
	s_add_u32 s0, s58, 0x0
	s_addc_u32 s1, s59, 0
	global_load_short_d16_hi v132, v175, s[0:1]
	global_load_short_d16_hi v133, v175, s[0:1] offset:2048
	s_add_u32 s0, s100, 0x1000
	s_addc_u32 s1, s101, 0
	global_load_short_d16_hi v126, v175, s[0:1]
	global_load_short_d16_hi v127, v175, s[0:1] offset:2048
	s_add_u32 s0, s58, 0x1000
	s_addc_u32 s1, s59, 0
	global_load_short_d16_hi v134, v175, s[0:1]
	global_load_short_d16_hi v135, v175, s[0:1] offset:2048
	s_add_u32 s0, s100, 0x2000
	s_addc_u32 s1, s101, 0
	global_load_short_d16_hi v128, v175, s[0:1]
	global_load_short_d16_hi v129, v175, s[0:1] offset:2048
	s_add_u32 s0, s58, 0x2000
	s_addc_u32 s1, s59, 0
	global_load_short_d16_hi v136, v175, s[0:1]
	global_load_short_d16_hi v137, v175, s[0:1] offset:2048
	s_add_u32 s0, s100, 0x3000
	s_addc_u32 s1, s101, 0
	global_load_short_d16_hi v130, v175, s[0:1]
	global_load_short_d16_hi v131, v175, s[0:1] offset:2048
	s_add_u32 s0, s58, 0x3000
	s_addc_u32 s1, s59, 0
	global_load_short_d16_hi v138, v175, s[0:1]
	global_load_short_d16_hi v139, v175, s[0:1] offset:2048
	s_add_u32 s98, s98, 0xa4000
	s_addc_u32 s99, s99, 0
	s_add_u32 s100, s100, 0x10000
	s_addc_u32 s101, s101, 0
	s_add_u32 s58, s58, 0x10000
	s_addc_u32 s59, s59, 0
	s_waitcnt vmcnt(0)
	v_sub_f32_e32 v221, 1.0, v200
	s_mov_b32 s0, 0
	s_waitcnt vmcnt(0)
	v_add_u32_e32 v222, s0, v224
	v_add_u32_e32 v223, s0, v225
	s_mov_b64 s[6:7], s[14:15]
	v_mul_f32_e32 v204, 0xbfb8aa3b, v124
	v_sub_f32_e32 v208, v172, v100
	v_exp_f32_e32 v211, v204
	v_sub_f32_e32 v209, v173, v108
	v_sub_f32_e32 v210, v174, v116
	v_fma_f32 v208, v196, v208, v100
	v_fma_f32 v209, v197, v209, v108
	v_fma_f32 v210, v198, v210, v116
	v_mul_f32_e32 v213, v209, v199
	v_fma_f32 v214, v132, v200, v221
	v_mul_f32_e32 v215, v209, v214
	v_mul_f32_e32 v227, v213, v213
	v_mul_f32_e32 v228, v213, v132
	v_mul_f32_e32 v229, v215, v208
	v_mul_f32_e32 v228, v228, v208
	v_mul_f32_e32 v230, v229, v226
	v_add_f32_dpp v227, v227, v227 quad_perm:[1,0,3,2] row_mask:0xf bank_mask:0xf bound_ctrl:1
	v_add_f32_dpp v228, v228, v228 quad_perm:[1,0,3,2] row_mask:0xf bank_mask:0xf bound_ctrl:1
	v_add_f32_dpp v229, v229, v229 quad_perm:[1,0,3,2] row_mask:0xf bank_mask:0xf bound_ctrl:1
	v_add_f32_dpp v230, v230, v230 quad_perm:[1,0,3,2] row_mask:0xf bank_mask:0xf bound_ctrl:1
	v_add_f32_dpp v227, v227, v227 quad_perm:[2,3,0,1] row_mask:0xf bank_mask:0xf bound_ctrl:1
	v_add_f32_dpp v228, v228, v228 quad_perm:[2,3,0,1] row_mask:0xf bank_mask:0xf bound_ctrl:1
	v_add_f32_dpp v229, v229, v229 quad_perm:[2,3,0,1] row_mask:0xf bank_mask:0xf bound_ctrl:1
	v_add_f32_dpp v230, v230, v230 quad_perm:[2,3,0,1] row_mask:0xf bank_mask:0xf bound_ctrl:1
	v_add_f32_dpp v227, v227, v227 row_half_mirror row_mask:0xf bank_mask:0xf bound_ctrl:1
	v_add_f32_dpp v228, v228, v228 row_half_mirror row_mask:0xf bank_mask:0xf bound_ctrl:1
	v_add_f32_dpp v229, v229, v229 row_half_mirror row_mask:0xf bank_mask:0xf bound_ctrl:1
	v_add_f32_dpp v230, v230, v230 row_half_mirror row_mask:0xf bank_mask:0xf bound_ctrl:1
	v_add_f32_dpp v227, v227, v227 row_mirror row_mask:0xf bank_mask:0xf bound_ctrl:1
	v_add_f32_dpp v228, v228, v228 row_mirror row_mask:0xf bank_mask:0xf bound_ctrl:1
	v_add_f32_dpp v229, v229, v229 row_mirror row_mask:0xf bank_mask:0xf bound_ctrl:1
	v_add_f32_dpp v230, v230, v230 row_mirror row_mask:0xf bank_mask:0xf bound_ctrl:1
	v_add_f32_dpp v227, v227, v227 row_bcast:15 row_mask:0xa bank_mask:0xf
	v_add_f32_dpp v228, v228, v228 row_bcast:15 row_mask:0xa bank_mask:0xf
	v_add_f32_dpp v229, v229, v229 row_bcast:15 row_mask:0xa bank_mask:0xf
	v_add_f32_dpp v230, v230, v230 row_bcast:15 row_mask:0xa bank_mask:0xf
	v_add_f32_dpp v227, v227, v227 row_bcast:31 row_mask:0xc bank_mask:0xf
	v_add_f32_dpp v228, v228, v228 row_bcast:31 row_mask:0xc bank_mask:0xf
	v_add_f32_dpp v229, v229, v229 row_bcast:31 row_mask:0xc bank_mask:0xf
	v_add_f32_dpp v230, v230, v230 row_bcast:31 row_mask:0xc bank_mask:0xf
	v_readlane_b32 s0, v227, 63
	v_readlane_b32 s1, v228, 63
	v_readlane_b32 s33, v229, 63
	v_readlane_b32 s41, v230, 63
	v_mov_b32_e32 v231, s0
	v_mov_b32_e32 v234, s33
	v_sqrt_f32_e32 v231, v231
	v_mul_f32_e32 v235, s41, v210
	v_max_f32_e32 v231, 0x2b8cbccc, v231
	v_rcp_f32_e32 v231, v231
	v_cvt_pk_bf16_f32 v235, v235, v235
	v_mul_f32_e32 v213, v213, v231
	v_mul_f32_e32 v233, s1, v231
	v_mul_f32_e32 v217, -1.0, v213
	v_rcp_f32_e32 v212, v211
	v_mul_f32_e32 v216, v213, v132
	v_mul_f32_e32 v218, v211, v208
	v_fmac_f32_e32 v218, v233, v217
	ds_write2st64_b32 v222, v217, v218 offset0:0 offset1:1
	v_mul_f32_e32 v219, v216, v212
	v_mul_f32_e32 v220, v215, v212
	ds_write2st64_b32 v222, v211, v219 offset0:2 offset1:3
	ds_write_b32 v222, v220 offset:1024
	ds_write_b32 v223, v210 offset:0
	ds_write_b32 v223, v234 offset:8
	s_bitcmp1_b32 s72, 0
	s_cbranch_scc1 .Lrwq_nobv_0_p
	global_store_short v175, v235, s[6:7]
.Lrwq_nobv_0_p:
	s_add_u32 s6, s6, 0x5200
	s_addc_u32 s7, s7, 0
	v_mul_f32_e32 v204, 0xbfb8aa3b, v125
	v_sub_f32_e32 v208, v100, v101
	v_exp_f32_e32 v206, v204
	v_sub_f32_e32 v209, v108, v109
	v_sub_f32_e32 v210, v116, v117
	v_fma_f32 v208, v196, v208, v101
	v_fma_f32 v209, v197, v209, v109
	v_fma_f32 v210, v198, v210, v117
	v_mul_f32_e32 v213, v209, v199
	v_fma_f32 v214, v133, v200, v221
	v_mul_f32_e32 v215, v209, v214
	v_mul_f32_e32 v227, v213, v213
	v_mul_f32_e32 v228, v213, v133
	v_mul_f32_e32 v229, v215, v208
	v_mul_f32_e32 v228, v228, v208
	v_mul_f32_e32 v230, v229, v226
	v_add_f32_dpp v227, v227, v227 quad_perm:[1,0,3,2] row_mask:0xf bank_mask:0xf bound_ctrl:1
	v_add_f32_dpp v228, v228, v228 quad_perm:[1,0,3,2] row_mask:0xf bank_mask:0xf bound_ctrl:1
	v_add_f32_dpp v229, v229, v229 quad_perm:[1,0,3,2] row_mask:0xf bank_mask:0xf bound_ctrl:1
	v_add_f32_dpp v230, v230, v230 quad_perm:[1,0,3,2] row_mask:0xf bank_mask:0xf bound_ctrl:1
	v_add_f32_dpp v227, v227, v227 quad_perm:[2,3,0,1] row_mask:0xf bank_mask:0xf bound_ctrl:1
	v_add_f32_dpp v228, v228, v228 quad_perm:[2,3,0,1] row_mask:0xf bank_mask:0xf bound_ctrl:1
	v_add_f32_dpp v229, v229, v229 quad_perm:[2,3,0,1] row_mask:0xf bank_mask:0xf bound_ctrl:1
	v_add_f32_dpp v230, v230, v230 quad_perm:[2,3,0,1] row_mask:0xf bank_mask:0xf bound_ctrl:1
	v_add_f32_dpp v227, v227, v227 row_half_mirror row_mask:0xf bank_mask:0xf bound_ctrl:1
	v_add_f32_dpp v228, v228, v228 row_half_mirror row_mask:0xf bank_mask:0xf bound_ctrl:1
	v_add_f32_dpp v229, v229, v229 row_half_mirror row_mask:0xf bank_mask:0xf bound_ctrl:1
	v_add_f32_dpp v230, v230, v230 row_half_mirror row_mask:0xf bank_mask:0xf bound_ctrl:1
	v_add_f32_dpp v227, v227, v227 row_mirror row_mask:0xf bank_mask:0xf bound_ctrl:1
	v_add_f32_dpp v228, v228, v228 row_mirror row_mask:0xf bank_mask:0xf bound_ctrl:1
	v_add_f32_dpp v229, v229, v229 row_mirror row_mask:0xf bank_mask:0xf bound_ctrl:1
	v_add_f32_dpp v230, v230, v230 row_mirror row_mask:0xf bank_mask:0xf bound_ctrl:1
	v_add_f32_dpp v227, v227, v227 row_bcast:15 row_mask:0xa bank_mask:0xf
	v_add_f32_dpp v228, v228, v228 row_bcast:15 row_mask:0xa bank_mask:0xf
	v_add_f32_dpp v229, v229, v229 row_bcast:15 row_mask:0xa bank_mask:0xf
	v_add_f32_dpp v230, v230, v230 row_bcast:15 row_mask:0xa bank_mask:0xf
	v_add_f32_dpp v227, v227, v227 row_bcast:31 row_mask:0xc bank_mask:0xf
	v_add_f32_dpp v228, v228, v228 row_bcast:31 row_mask:0xc bank_mask:0xf
	v_add_f32_dpp v229, v229, v229 row_bcast:31 row_mask:0xc bank_mask:0xf
	v_add_f32_dpp v230, v230, v230 row_bcast:31 row_mask:0xc bank_mask:0xf
	v_readlane_b32 s0, v227, 63
	v_readlane_b32 s1, v228, 63
	v_readlane_b32 s33, v229, 63
	v_readlane_b32 s41, v230, 63
	v_mov_b32_e32 v231, s0
	v_mov_b32_e32 v234, s33
	v_sqrt_f32_e32 v231, v231
	v_mul_f32_e32 v235, s41, v210
	v_max_f32_e32 v231, 0x2b8cbccc, v231
	v_rcp_f32_e32 v231, v231
	v_cvt_pk_bf16_f32 v235, v235, v235
	v_mul_f32_e32 v213, v213, v231
	v_mul_f32_e32 v233, s1, v231
	v_mul_f32_e64 v217, -v213, v211
	v_mul_f32_e32 v211, v211, v206
	v_rcp_f32_e32 v212, v211
	v_mul_f32_e32 v216, v213, v133
	v_mul_f32_e32 v218, v211, v208
	v_fmac_f32_e32 v218, v233, v217
	ds_write2st64_b32 v222, v217, v218 offset0:7 offset1:8
	v_mul_f32_e32 v219, v216, v212
	v_mul_f32_e32 v220, v215, v212
	ds_write2st64_b32 v222, v211, v219 offset0:9 offset1:10
	ds_write_b32 v222, v220 offset:2816
	ds_write_b32 v223, v210 offset:1792
	ds_write_b32 v223, v234 offset:1800
	s_bitcmp1_b32 s72, 0
	s_cbranch_scc1 .Lrwq_nobv_1_p
	global_store_short v175, v235, s[6:7]
.Lrwq_nobv_1_p:
	s_add_u32 s6, s6, 0x5200
	s_addc_u32 s7, s7, 0
	v_mul_f32_e32 v204, 0xbfb8aa3b, v126
	v_sub_f32_e32 v208, v101, v102
	v_exp_f32_e32 v206, v204
	v_sub_f32_e32 v209, v109, v110
	v_sub_f32_e32 v210, v117, v118
	v_fma_f32 v208, v196, v208, v102
	v_fma_f32 v209, v197, v209, v110
	v_fma_f32 v210, v198, v210, v118
	v_mul_f32_e32 v213, v209, v199
	v_fma_f32 v214, v134, v200, v221
	v_mul_f32_e32 v215, v209, v214
	v_mul_f32_e32 v227, v213, v213
	v_mul_f32_e32 v228, v213, v134
	v_mul_f32_e32 v229, v215, v208
	v_mul_f32_e32 v228, v228, v208
	v_mul_f32_e32 v230, v229, v226
	v_add_f32_dpp v227, v227, v227 quad_perm:[1,0,3,2] row_mask:0xf bank_mask:0xf bound_ctrl:1
	v_add_f32_dpp v228, v228, v228 quad_perm:[1,0,3,2] row_mask:0xf bank_mask:0xf bound_ctrl:1
	v_add_f32_dpp v229, v229, v229 quad_perm:[1,0,3,2] row_mask:0xf bank_mask:0xf bound_ctrl:1
	v_add_f32_dpp v230, v230, v230 quad_perm:[1,0,3,2] row_mask:0xf bank_mask:0xf bound_ctrl:1
	v_add_f32_dpp v227, v227, v227 quad_perm:[2,3,0,1] row_mask:0xf bank_mask:0xf bound_ctrl:1
	v_add_f32_dpp v228, v228, v228 quad_perm:[2,3,0,1] row_mask:0xf bank_mask:0xf bound_ctrl:1
	v_add_f32_dpp v229, v229, v229 quad_perm:[2,3,0,1] row_mask:0xf bank_mask:0xf bound_ctrl:1
	v_add_f32_dpp v230, v230, v230 quad_perm:[2,3,0,1] row_mask:0xf bank_mask:0xf bound_ctrl:1
	v_add_f32_dpp v227, v227, v227 row_half_mirror row_mask:0xf bank_mask:0xf bound_ctrl:1
	v_add_f32_dpp v228, v228, v228 row_half_mirror row_mask:0xf bank_mask:0xf bound_ctrl:1
	v_add_f32_dpp v229, v229, v229 row_half_mirror row_mask:0xf bank_mask:0xf bound_ctrl:1
	v_add_f32_dpp v230, v230, v230 row_half_mirror row_mask:0xf bank_mask:0xf bound_ctrl:1
	v_add_f32_dpp v227, v227, v227 row_mirror row_mask:0xf bank_mask:0xf bound_ctrl:1
	v_add_f32_dpp v228, v228, v228 row_mirror row_mask:0xf bank_mask:0xf bound_ctrl:1
	v_add_f32_dpp v229, v229, v229 row_mirror row_mask:0xf bank_mask:0xf bound_ctrl:1
	v_add_f32_dpp v230, v230, v230 row_mirror row_mask:0xf bank_mask:0xf bound_ctrl:1
	v_add_f32_dpp v227, v227, v227 row_bcast:15 row_mask:0xa bank_mask:0xf
	v_add_f32_dpp v228, v228, v228 row_bcast:15 row_mask:0xa bank_mask:0xf
	v_add_f32_dpp v229, v229, v229 row_bcast:15 row_mask:0xa bank_mask:0xf
	v_add_f32_dpp v230, v230, v230 row_bcast:15 row_mask:0xa bank_mask:0xf
	v_add_f32_dpp v227, v227, v227 row_bcast:31 row_mask:0xc bank_mask:0xf
	v_add_f32_dpp v228, v228, v228 row_bcast:31 row_mask:0xc bank_mask:0xf
	v_add_f32_dpp v229, v229, v229 row_bcast:31 row_mask:0xc bank_mask:0xf
	v_add_f32_dpp v230, v230, v230 row_bcast:31 row_mask:0xc bank_mask:0xf
	v_readlane_b32 s0, v227, 63
	v_readlane_b32 s1, v228, 63
	v_readlane_b32 s33, v229, 63
	v_readlane_b32 s41, v230, 63
	v_mov_b32_e32 v231, s0
	v_mov_b32_e32 v234, s33
	v_sqrt_f32_e32 v231, v231
	v_mul_f32_e32 v235, s41, v210
	v_max_f32_e32 v231, 0x2b8cbccc, v231
	v_rcp_f32_e32 v231, v231
	v_cvt_pk_bf16_f32 v235, v235, v235
	v_mul_f32_e32 v213, v213, v231
	v_mul_f32_e32 v233, s1, v231
	v_mul_f32_e64 v217, -v213, v211
	v_mul_f32_e32 v211, v211, v206
	v_rcp_f32_e32 v212, v211
	v_mul_f32_e32 v216, v213, v134
	v_mul_f32_e32 v218, v211, v208
	v_fmac_f32_e32 v218, v233, v217
	ds_write2st64_b32 v222, v217, v218 offset0:14 offset1:15
	v_mul_f32_e32 v219, v216, v212
	v_mul_f32_e32 v220, v215, v212
	ds_write2st64_b32 v222, v211, v219 offset0:16 offset1:17
	ds_write_b32 v222, v220 offset:4608
	ds_write_b32 v223, v210 offset:3584
	ds_write_b32 v223, v234 offset:3592
	s_bitcmp1_b32 s72, 0
	s_cbranch_scc1 .Lrwq_nobv_2_p
	global_store_short v175, v235, s[6:7]
.Lrwq_nobv_2_p:
	s_add_u32 s6, s6, 0x5200
	s_addc_u32 s7, s7, 0
	v_mul_f32_e32 v204, 0xbfb8aa3b, v127
	v_sub_f32_e32 v208, v102, v103
	v_exp_f32_e32 v206, v204
	v_sub_f32_e32 v209, v110, v111
	v_sub_f32_e32 v210, v118, v119
	v_fma_f32 v208, v196, v208, v103
	v_fma_f32 v209, v197, v209, v111
	v_fma_f32 v210, v198, v210, v119
	v_mul_f32_e32 v213, v209, v199
	v_fma_f32 v214, v135, v200, v221
	v_mul_f32_e32 v215, v209, v214
	v_mul_f32_e32 v227, v213, v213
	v_mul_f32_e32 v228, v213, v135
	v_mul_f32_e32 v229, v215, v208
	v_mul_f32_e32 v228, v228, v208
	v_mul_f32_e32 v230, v229, v226
	v_add_f32_dpp v227, v227, v227 quad_perm:[1,0,3,2] row_mask:0xf bank_mask:0xf bound_ctrl:1
	v_add_f32_dpp v228, v228, v228 quad_perm:[1,0,3,2] row_mask:0xf bank_mask:0xf bound_ctrl:1
	v_add_f32_dpp v229, v229, v229 quad_perm:[1,0,3,2] row_mask:0xf bank_mask:0xf bound_ctrl:1
	v_add_f32_dpp v230, v230, v230 quad_perm:[1,0,3,2] row_mask:0xf bank_mask:0xf bound_ctrl:1
	v_add_f32_dpp v227, v227, v227 quad_perm:[2,3,0,1] row_mask:0xf bank_mask:0xf bound_ctrl:1
	v_add_f32_dpp v228, v228, v228 quad_perm:[2,3,0,1] row_mask:0xf bank_mask:0xf bound_ctrl:1
	v_add_f32_dpp v229, v229, v229 quad_perm:[2,3,0,1] row_mask:0xf bank_mask:0xf bound_ctrl:1
	v_add_f32_dpp v230, v230, v230 quad_perm:[2,3,0,1] row_mask:0xf bank_mask:0xf bound_ctrl:1
	v_add_f32_dpp v227, v227, v227 row_half_mirror row_mask:0xf bank_mask:0xf bound_ctrl:1
	v_add_f32_dpp v228, v228, v228 row_half_mirror row_mask:0xf bank_mask:0xf bound_ctrl:1
	v_add_f32_dpp v229, v229, v229 row_half_mirror row_mask:0xf bank_mask:0xf bound_ctrl:1
	v_add_f32_dpp v230, v230, v230 row_half_mirror row_mask:0xf bank_mask:0xf bound_ctrl:1
	v_add_f32_dpp v227, v227, v227 row_mirror row_mask:0xf bank_mask:0xf bound_ctrl:1
	v_add_f32_dpp v228, v228, v228 row_mirror row_mask:0xf bank_mask:0xf bound_ctrl:1
	v_add_f32_dpp v229, v229, v229 row_mirror row_mask:0xf bank_mask:0xf bound_ctrl:1
	v_add_f32_dpp v230, v230, v230 row_mirror row_mask:0xf bank_mask:0xf bound_ctrl:1
	v_add_f32_dpp v227, v227, v227 row_bcast:15 row_mask:0xa bank_mask:0xf
	v_add_f32_dpp v228, v228, v228 row_bcast:15 row_mask:0xa bank_mask:0xf
	v_add_f32_dpp v229, v229, v229 row_bcast:15 row_mask:0xa bank_mask:0xf
	v_add_f32_dpp v230, v230, v230 row_bcast:15 row_mask:0xa bank_mask:0xf
	v_add_f32_dpp v227, v227, v227 row_bcast:31 row_mask:0xc bank_mask:0xf
	v_add_f32_dpp v228, v228, v228 row_bcast:31 row_mask:0xc bank_mask:0xf
	v_add_f32_dpp v229, v229, v229 row_bcast:31 row_mask:0xc bank_mask:0xf
	v_add_f32_dpp v230, v230, v230 row_bcast:31 row_mask:0xc bank_mask:0xf
	v_readlane_b32 s0, v227, 63
	v_readlane_b32 s1, v228, 63
	v_readlane_b32 s33, v229, 63
	v_readlane_b32 s41, v230, 63
	v_mov_b32_e32 v231, s0
	v_mov_b32_e32 v234, s33
	v_sqrt_f32_e32 v231, v231
	v_mul_f32_e32 v235, s41, v210
	v_max_f32_e32 v231, 0x2b8cbccc, v231
	v_rcp_f32_e32 v231, v231
	v_cvt_pk_bf16_f32 v235, v235, v235
	v_mul_f32_e32 v213, v213, v231
	v_mul_f32_e32 v233, s1, v231
	v_mul_f32_e64 v217, -v213, v211
	v_mul_f32_e32 v211, v211, v206
	v_rcp_f32_e32 v212, v211
	v_mul_f32_e32 v216, v213, v135
	v_mul_f32_e32 v218, v211, v208
	v_fmac_f32_e32 v218, v233, v217
	ds_write2st64_b32 v222, v217, v218 offset0:21 offset1:22
	v_mul_f32_e32 v219, v216, v212
	v_mul_f32_e32 v220, v215, v212
	ds_write2st64_b32 v222, v211, v219 offset0:23 offset1:24
	ds_write_b32 v222, v220 offset:6400
	ds_write_b32 v223, v210 offset:5376
	ds_write_b32 v223, v234 offset:5384
	s_bitcmp1_b32 s72, 0
	s_cbranch_scc1 .Lrwq_nobv_3_p
	global_store_short v175, v235, s[6:7]
.Lrwq_nobv_3_p:
	s_add_u32 s6, s6, 0x5200
	s_addc_u32 s7, s7, 0
	v_mul_f32_e32 v204, 0xbfb8aa3b, v128
	v_sub_f32_e32 v208, v103, v104
	v_exp_f32_e32 v206, v204
	v_sub_f32_e32 v209, v111, v112
	v_sub_f32_e32 v210, v119, v120
	v_fma_f32 v208, v196, v208, v104
	v_fma_f32 v209, v197, v209, v112
	v_fma_f32 v210, v198, v210, v120
	v_mul_f32_e32 v213, v209, v199
	v_fma_f32 v214, v136, v200, v221
	v_mul_f32_e32 v215, v209, v214
	v_mul_f32_e32 v227, v213, v213
	v_mul_f32_e32 v228, v213, v136
	v_mul_f32_e32 v229, v215, v208
	v_mul_f32_e32 v228, v228, v208
	v_mul_f32_e32 v230, v229, v226
	v_add_f32_dpp v227, v227, v227 quad_perm:[1,0,3,2] row_mask:0xf bank_mask:0xf bound_ctrl:1
	v_add_f32_dpp v228, v228, v228 quad_perm:[1,0,3,2] row_mask:0xf bank_mask:0xf bound_ctrl:1
	v_add_f32_dpp v229, v229, v229 quad_perm:[1,0,3,2] row_mask:0xf bank_mask:0xf bound_ctrl:1
	v_add_f32_dpp v230, v230, v230 quad_perm:[1,0,3,2] row_mask:0xf bank_mask:0xf bound_ctrl:1
	v_add_f32_dpp v227, v227, v227 quad_perm:[2,3,0,1] row_mask:0xf bank_mask:0xf bound_ctrl:1
	v_add_f32_dpp v228, v228, v228 quad_perm:[2,3,0,1] row_mask:0xf bank_mask:0xf bound_ctrl:1
	v_add_f32_dpp v229, v229, v229 quad_perm:[2,3,0,1] row_mask:0xf bank_mask:0xf bound_ctrl:1
	v_add_f32_dpp v230, v230, v230 quad_perm:[2,3,0,1] row_mask:0xf bank_mask:0xf bound_ctrl:1
	v_add_f32_dpp v227, v227, v227 row_half_mirror row_mask:0xf bank_mask:0xf bound_ctrl:1
	v_add_f32_dpp v228, v228, v228 row_half_mirror row_mask:0xf bank_mask:0xf bound_ctrl:1
	v_add_f32_dpp v229, v229, v229 row_half_mirror row_mask:0xf bank_mask:0xf bound_ctrl:1
	v_add_f32_dpp v230, v230, v230 row_half_mirror row_mask:0xf bank_mask:0xf bound_ctrl:1
	v_add_f32_dpp v227, v227, v227 row_mirror row_mask:0xf bank_mask:0xf bound_ctrl:1
	v_add_f32_dpp v228, v228, v228 row_mirror row_mask:0xf bank_mask:0xf bound_ctrl:1
	v_add_f32_dpp v229, v229, v229 row_mirror row_mask:0xf bank_mask:0xf bound_ctrl:1
	v_add_f32_dpp v230, v230, v230 row_mirror row_mask:0xf bank_mask:0xf bound_ctrl:1
	v_add_f32_dpp v227, v227, v227 row_bcast:15 row_mask:0xa bank_mask:0xf
	v_add_f32_dpp v228, v228, v228 row_bcast:15 row_mask:0xa bank_mask:0xf
	v_add_f32_dpp v229, v229, v229 row_bcast:15 row_mask:0xa bank_mask:0xf
	v_add_f32_dpp v230, v230, v230 row_bcast:15 row_mask:0xa bank_mask:0xf
	v_add_f32_dpp v227, v227, v227 row_bcast:31 row_mask:0xc bank_mask:0xf
	v_add_f32_dpp v228, v228, v228 row_bcast:31 row_mask:0xc bank_mask:0xf
	v_add_f32_dpp v229, v229, v229 row_bcast:31 row_mask:0xc bank_mask:0xf
	v_add_f32_dpp v230, v230, v230 row_bcast:31 row_mask:0xc bank_mask:0xf
	v_readlane_b32 s0, v227, 63
	v_readlane_b32 s1, v228, 63
	v_readlane_b32 s33, v229, 63
	v_readlane_b32 s41, v230, 63
	v_mov_b32_e32 v231, s0
	v_mov_b32_e32 v234, s33
	v_sqrt_f32_e32 v231, v231
	v_mul_f32_e32 v235, s41, v210
	v_max_f32_e32 v231, 0x2b8cbccc, v231
	v_rcp_f32_e32 v231, v231
	v_cvt_pk_bf16_f32 v235, v235, v235
	v_mul_f32_e32 v213, v213, v231
	v_mul_f32_e32 v233, s1, v231
	v_mul_f32_e64 v217, -v213, v211
	v_mul_f32_e32 v211, v211, v206
	v_rcp_f32_e32 v212, v211
	v_mul_f32_e32 v216, v213, v136
	v_mul_f32_e32 v218, v211, v208
	v_fmac_f32_e32 v218, v233, v217
	ds_write2st64_b32 v222, v217, v218 offset0:28 offset1:29
	v_mul_f32_e32 v219, v216, v212
	v_mul_f32_e32 v220, v215, v212
	ds_write2st64_b32 v222, v211, v219 offset0:30 offset1:31
	ds_write_b32 v222, v220 offset:8192
	ds_write_b32 v223, v210 offset:7168
	ds_write_b32 v223, v234 offset:7176
	s_bitcmp1_b32 s72, 0
	s_cbranch_scc1 .Lrwq_nobv_4_p
	global_store_short v175, v235, s[6:7]
.Lrwq_nobv_4_p:
	s_add_u32 s6, s6, 0x5200
	s_addc_u32 s7, s7, 0
	v_mul_f32_e32 v204, 0xbfb8aa3b, v129
	v_sub_f32_e32 v208, v104, v105
	v_exp_f32_e32 v206, v204
	v_sub_f32_e32 v209, v112, v113
	v_sub_f32_e32 v210, v120, v121
	v_fma_f32 v208, v196, v208, v105
	v_fma_f32 v209, v197, v209, v113
	v_fma_f32 v210, v198, v210, v121
	v_mul_f32_e32 v213, v209, v199
	v_fma_f32 v214, v137, v200, v221
	v_mul_f32_e32 v215, v209, v214
	v_mul_f32_e32 v227, v213, v213
	v_mul_f32_e32 v228, v213, v137
	v_mul_f32_e32 v229, v215, v208
	v_mul_f32_e32 v228, v228, v208
	v_mul_f32_e32 v230, v229, v226
	v_add_f32_dpp v227, v227, v227 quad_perm:[1,0,3,2] row_mask:0xf bank_mask:0xf bound_ctrl:1
	v_add_f32_dpp v228, v228, v228 quad_perm:[1,0,3,2] row_mask:0xf bank_mask:0xf bound_ctrl:1
	v_add_f32_dpp v229, v229, v229 quad_perm:[1,0,3,2] row_mask:0xf bank_mask:0xf bound_ctrl:1
	v_add_f32_dpp v230, v230, v230 quad_perm:[1,0,3,2] row_mask:0xf bank_mask:0xf bound_ctrl:1
	v_add_f32_dpp v227, v227, v227 quad_perm:[2,3,0,1] row_mask:0xf bank_mask:0xf bound_ctrl:1
	v_add_f32_dpp v228, v228, v228 quad_perm:[2,3,0,1] row_mask:0xf bank_mask:0xf bound_ctrl:1
	v_add_f32_dpp v229, v229, v229 quad_perm:[2,3,0,1] row_mask:0xf bank_mask:0xf bound_ctrl:1
	v_add_f32_dpp v230, v230, v230 quad_perm:[2,3,0,1] row_mask:0xf bank_mask:0xf bound_ctrl:1
	v_add_f32_dpp v227, v227, v227 row_half_mirror row_mask:0xf bank_mask:0xf bound_ctrl:1
	v_add_f32_dpp v228, v228, v228 row_half_mirror row_mask:0xf bank_mask:0xf bound_ctrl:1
	v_add_f32_dpp v229, v229, v229 row_half_mirror row_mask:0xf bank_mask:0xf bound_ctrl:1
	v_add_f32_dpp v230, v230, v230 row_half_mirror row_mask:0xf bank_mask:0xf bound_ctrl:1
	v_add_f32_dpp v227, v227, v227 row_mirror row_mask:0xf bank_mask:0xf bound_ctrl:1
	v_add_f32_dpp v228, v228, v228 row_mirror row_mask:0xf bank_mask:0xf bound_ctrl:1
	v_add_f32_dpp v229, v229, v229 row_mirror row_mask:0xf bank_mask:0xf bound_ctrl:1
	v_add_f32_dpp v230, v230, v230 row_mirror row_mask:0xf bank_mask:0xf bound_ctrl:1
	v_add_f32_dpp v227, v227, v227 row_bcast:15 row_mask:0xa bank_mask:0xf
	v_add_f32_dpp v228, v228, v228 row_bcast:15 row_mask:0xa bank_mask:0xf
	v_add_f32_dpp v229, v229, v229 row_bcast:15 row_mask:0xa bank_mask:0xf
	v_add_f32_dpp v230, v230, v230 row_bcast:15 row_mask:0xa bank_mask:0xf
	v_add_f32_dpp v227, v227, v227 row_bcast:31 row_mask:0xc bank_mask:0xf
	v_add_f32_dpp v228, v228, v228 row_bcast:31 row_mask:0xc bank_mask:0xf
	v_add_f32_dpp v229, v229, v229 row_bcast:31 row_mask:0xc bank_mask:0xf
	v_add_f32_dpp v230, v230, v230 row_bcast:31 row_mask:0xc bank_mask:0xf
	v_readlane_b32 s0, v227, 63
	v_readlane_b32 s1, v228, 63
	v_readlane_b32 s33, v229, 63
	v_readlane_b32 s41, v230, 63
	v_mov_b32_e32 v231, s0
	v_mov_b32_e32 v234, s33
	v_sqrt_f32_e32 v231, v231
	v_mul_f32_e32 v235, s41, v210
	v_max_f32_e32 v231, 0x2b8cbccc, v231
	v_rcp_f32_e32 v231, v231
	v_cvt_pk_bf16_f32 v235, v235, v235
	v_mul_f32_e32 v213, v213, v231
	v_mul_f32_e32 v233, s1, v231
	v_mul_f32_e64 v217, -v213, v211
	v_mul_f32_e32 v211, v211, v206
	v_rcp_f32_e32 v212, v211
	v_mul_f32_e32 v216, v213, v137
	v_mul_f32_e32 v218, v211, v208
	v_fmac_f32_e32 v218, v233, v217
	ds_write2st64_b32 v222, v217, v218 offset0:35 offset1:36
	v_mul_f32_e32 v219, v216, v212
	v_mul_f32_e32 v220, v215, v212
	ds_write2st64_b32 v222, v211, v219 offset0:37 offset1:38
	ds_write_b32 v222, v220 offset:9984
	ds_write_b32 v223, v210 offset:8960
	ds_write_b32 v223, v234 offset:8968
	s_bitcmp1_b32 s72, 0
	s_cbranch_scc1 .Lrwq_nobv_5_p
	global_store_short v175, v235, s[6:7]
.Lrwq_nobv_5_p:
	s_add_u32 s6, s6, 0x5200
	s_addc_u32 s7, s7, 0
	v_mul_f32_e32 v204, 0xbfb8aa3b, v130
	v_sub_f32_e32 v208, v105, v106
	v_exp_f32_e32 v206, v204
	v_sub_f32_e32 v209, v113, v114
	v_sub_f32_e32 v210, v121, v122
	v_fma_f32 v208, v196, v208, v106
	v_fma_f32 v209, v197, v209, v114
	v_fma_f32 v210, v198, v210, v122
	v_mul_f32_e32 v213, v209, v199
	v_fma_f32 v214, v138, v200, v221
	v_mul_f32_e32 v215, v209, v214
	v_mul_f32_e32 v227, v213, v213
	v_mul_f32_e32 v228, v213, v138
	v_mul_f32_e32 v229, v215, v208
	v_mul_f32_e32 v228, v228, v208
	v_mul_f32_e32 v230, v229, v226
	v_add_f32_dpp v227, v227, v227 quad_perm:[1,0,3,2] row_mask:0xf bank_mask:0xf bound_ctrl:1
	v_add_f32_dpp v228, v228, v228 quad_perm:[1,0,3,2] row_mask:0xf bank_mask:0xf bound_ctrl:1
	v_add_f32_dpp v229, v229, v229 quad_perm:[1,0,3,2] row_mask:0xf bank_mask:0xf bound_ctrl:1
	v_add_f32_dpp v230, v230, v230 quad_perm:[1,0,3,2] row_mask:0xf bank_mask:0xf bound_ctrl:1
	v_add_f32_dpp v227, v227, v227 quad_perm:[2,3,0,1] row_mask:0xf bank_mask:0xf bound_ctrl:1
	v_add_f32_dpp v228, v228, v228 quad_perm:[2,3,0,1] row_mask:0xf bank_mask:0xf bound_ctrl:1
	v_add_f32_dpp v229, v229, v229 quad_perm:[2,3,0,1] row_mask:0xf bank_mask:0xf bound_ctrl:1
	v_add_f32_dpp v230, v230, v230 quad_perm:[2,3,0,1] row_mask:0xf bank_mask:0xf bound_ctrl:1
	v_add_f32_dpp v227, v227, v227 row_half_mirror row_mask:0xf bank_mask:0xf bound_ctrl:1
	v_add_f32_dpp v228, v228, v228 row_half_mirror row_mask:0xf bank_mask:0xf bound_ctrl:1
	v_add_f32_dpp v229, v229, v229 row_half_mirror row_mask:0xf bank_mask:0xf bound_ctrl:1
	v_add_f32_dpp v230, v230, v230 row_half_mirror row_mask:0xf bank_mask:0xf bound_ctrl:1
	v_add_f32_dpp v227, v227, v227 row_mirror row_mask:0xf bank_mask:0xf bound_ctrl:1
	v_add_f32_dpp v228, v228, v228 row_mirror row_mask:0xf bank_mask:0xf bound_ctrl:1
	v_add_f32_dpp v229, v229, v229 row_mirror row_mask:0xf bank_mask:0xf bound_ctrl:1
	v_add_f32_dpp v230, v230, v230 row_mirror row_mask:0xf bank_mask:0xf bound_ctrl:1
	v_add_f32_dpp v227, v227, v227 row_bcast:15 row_mask:0xa bank_mask:0xf
	v_add_f32_dpp v228, v228, v228 row_bcast:15 row_mask:0xa bank_mask:0xf
	v_add_f32_dpp v229, v229, v229 row_bcast:15 row_mask:0xa bank_mask:0xf
	v_add_f32_dpp v230, v230, v230 row_bcast:15 row_mask:0xa bank_mask:0xf
	v_add_f32_dpp v227, v227, v227 row_bcast:31 row_mask:0xc bank_mask:0xf
	v_add_f32_dpp v228, v228, v228 row_bcast:31 row_mask:0xc bank_mask:0xf
	v_add_f32_dpp v229, v229, v229 row_bcast:31 row_mask:0xc bank_mask:0xf
	v_add_f32_dpp v230, v230, v230 row_bcast:31 row_mask:0xc bank_mask:0xf
	v_readlane_b32 s0, v227, 63
	v_readlane_b32 s1, v228, 63
	v_readlane_b32 s33, v229, 63
	v_readlane_b32 s41, v230, 63
	v_mov_b32_e32 v231, s0
	v_mov_b32_e32 v234, s33
	v_sqrt_f32_e32 v231, v231
	v_mul_f32_e32 v235, s41, v210
	v_max_f32_e32 v231, 0x2b8cbccc, v231
	v_rcp_f32_e32 v231, v231
	v_cvt_pk_bf16_f32 v235, v235, v235
	v_mul_f32_e32 v213, v213, v231
	v_mul_f32_e32 v233, s1, v231
	v_mul_f32_e64 v217, -v213, v211
	v_mul_f32_e32 v211, v211, v206
	v_rcp_f32_e32 v212, v211
	v_mul_f32_e32 v216, v213, v138
	v_mul_f32_e32 v218, v211, v208
	v_fmac_f32_e32 v218, v233, v217
	ds_write2st64_b32 v222, v217, v218 offset0:42 offset1:43
	v_mul_f32_e32 v219, v216, v212
	v_mul_f32_e32 v220, v215, v212
	ds_write2st64_b32 v222, v211, v219 offset0:44 offset1:45
	ds_write_b32 v222, v220 offset:11776
	ds_write_b32 v223, v210 offset:10752
	ds_write_b32 v223, v234 offset:10760
	s_bitcmp1_b32 s72, 0
	s_cbranch_scc1 .Lrwq_nobv_6_p
	global_store_short v175, v235, s[6:7]
.Lrwq_nobv_6_p:
	s_add_u32 s6, s6, 0x5200
	s_addc_u32 s7, s7, 0
	v_mul_f32_e32 v204, 0xbfb8aa3b, v131
	v_sub_f32_e32 v208, v106, v107
	v_exp_f32_e32 v206, v204
	v_sub_f32_e32 v209, v114, v115
	v_sub_f32_e32 v210, v122, v123
	v_fma_f32 v208, v196, v208, v107
	v_fma_f32 v209, v197, v209, v115
	v_fma_f32 v210, v198, v210, v123
	v_mul_f32_e32 v213, v209, v199
	v_fma_f32 v214, v139, v200, v221
	v_mul_f32_e32 v215, v209, v214
	v_mul_f32_e32 v227, v213, v213
	v_mul_f32_e32 v228, v213, v139
	v_mul_f32_e32 v229, v215, v208
	v_mul_f32_e32 v228, v228, v208
	v_mul_f32_e32 v230, v229, v226
	v_add_f32_dpp v227, v227, v227 quad_perm:[1,0,3,2] row_mask:0xf bank_mask:0xf bound_ctrl:1
	v_add_f32_dpp v228, v228, v228 quad_perm:[1,0,3,2] row_mask:0xf bank_mask:0xf bound_ctrl:1
	v_add_f32_dpp v229, v229, v229 quad_perm:[1,0,3,2] row_mask:0xf bank_mask:0xf bound_ctrl:1
	v_add_f32_dpp v230, v230, v230 quad_perm:[1,0,3,2] row_mask:0xf bank_mask:0xf bound_ctrl:1
	v_add_f32_dpp v227, v227, v227 quad_perm:[2,3,0,1] row_mask:0xf bank_mask:0xf bound_ctrl:1
	v_add_f32_dpp v228, v228, v228 quad_perm:[2,3,0,1] row_mask:0xf bank_mask:0xf bound_ctrl:1
	v_add_f32_dpp v229, v229, v229 quad_perm:[2,3,0,1] row_mask:0xf bank_mask:0xf bound_ctrl:1
	v_add_f32_dpp v230, v230, v230 quad_perm:[2,3,0,1] row_mask:0xf bank_mask:0xf bound_ctrl:1
	v_add_f32_dpp v227, v227, v227 row_half_mirror row_mask:0xf bank_mask:0xf bound_ctrl:1
	v_add_f32_dpp v228, v228, v228 row_half_mirror row_mask:0xf bank_mask:0xf bound_ctrl:1
	v_add_f32_dpp v229, v229, v229 row_half_mirror row_mask:0xf bank_mask:0xf bound_ctrl:1
	v_add_f32_dpp v230, v230, v230 row_half_mirror row_mask:0xf bank_mask:0xf bound_ctrl:1
	v_add_f32_dpp v227, v227, v227 row_mirror row_mask:0xf bank_mask:0xf bound_ctrl:1
	v_add_f32_dpp v228, v228, v228 row_mirror row_mask:0xf bank_mask:0xf bound_ctrl:1
	v_add_f32_dpp v229, v229, v229 row_mirror row_mask:0xf bank_mask:0xf bound_ctrl:1
	v_add_f32_dpp v230, v230, v230 row_mirror row_mask:0xf bank_mask:0xf bound_ctrl:1
	v_add_f32_dpp v227, v227, v227 row_bcast:15 row_mask:0xa bank_mask:0xf
	v_add_f32_dpp v228, v228, v228 row_bcast:15 row_mask:0xa bank_mask:0xf
	v_add_f32_dpp v229, v229, v229 row_bcast:15 row_mask:0xa bank_mask:0xf
	v_add_f32_dpp v230, v230, v230 row_bcast:15 row_mask:0xa bank_mask:0xf
	v_add_f32_dpp v227, v227, v227 row_bcast:31 row_mask:0xc bank_mask:0xf
	v_add_f32_dpp v228, v228, v228 row_bcast:31 row_mask:0xc bank_mask:0xf
	v_add_f32_dpp v229, v229, v229 row_bcast:31 row_mask:0xc bank_mask:0xf
	v_add_f32_dpp v230, v230, v230 row_bcast:31 row_mask:0xc bank_mask:0xf
	v_readlane_b32 s0, v227, 63
	v_readlane_b32 s1, v228, 63
	v_readlane_b32 s33, v229, 63
	v_readlane_b32 s41, v230, 63
	v_mov_b32_e32 v231, s0
	v_mov_b32_e32 v234, s33
	v_sqrt_f32_e32 v231, v231
	v_mul_f32_e32 v235, s41, v210
	v_max_f32_e32 v231, 0x2b8cbccc, v231
	v_rcp_f32_e32 v231, v231
	v_cvt_pk_bf16_f32 v235, v235, v235
	v_mul_f32_e32 v213, v213, v231
	v_mul_f32_e32 v233, s1, v231
	v_mul_f32_e64 v217, -v213, v211
	v_mul_f32_e32 v211, v211, v206
	v_rcp_f32_e32 v212, v211
	v_mul_f32_e32 v216, v213, v139
	v_mul_f32_e32 v218, v211, v208
	v_fmac_f32_e32 v218, v233, v217
	ds_write2st64_b32 v222, v217, v218 offset0:49 offset1:50
	v_mul_f32_e32 v219, v216, v212
	v_mul_f32_e32 v220, v215, v212
	ds_write2st64_b32 v222, v211, v219 offset0:51 offset1:52
	ds_write_b32 v222, v220 offset:13568
	ds_write_b32 v223, v210 offset:12544
	ds_write_b32 v223, v234 offset:12552
	s_bitcmp1_b32 s72, 0
	s_cbranch_scc1 .Lrwq_nobv_7_p
	global_store_short v175, v235, s[6:7]

.LBB0_1348:
	s_and_saveexec_b64 s[0:1], s[16:17]
	s_xor_b64 s[56:57], exec, s[0:1]
	s_cbranch_execz .LBB0_1368
	s_cmp_eq_u32 s30, 63
	s_cbranch_scc1 .LBB0_1368
	s_andn2_b32 s0, 1, s30
	s_mul_i32 s0, s0, 0xe000
	s_waitcnt vmcnt(0)
	v_add_u32_e32 v222, s0, v224
	v_add_u32_e32 v223, s0, v225
	s_mov_b64 s[6:7], s[14:15]
	v_mul_f32_e32 v204, 0xbfb8aa3b, v124
	v_sub_f32_e32 v208, v172, v100
	v_exp_f32_e32 v211, v204
	v_sub_f32_e32 v209, v173, v108
	v_sub_f32_e32 v210, v174, v116
	v_fma_f32 v208, v196, v208, v100
	v_fma_f32 v209, v197, v209, v108
	v_fma_f32 v210, v198, v210, v116
	v_mul_f32_e32 v213, v209, v199
	v_fma_f32 v214, v132, v200, v221
	v_mul_f32_e32 v215, v209, v214
	v_mul_f32_e32 v227, v213, v213
	v_mul_f32_e32 v228, v213, v132
	v_mul_f32_e32 v229, v215, v208
	v_mul_f32_e32 v228, v228, v208
	v_mul_f32_e32 v230, v229, v226
	v_add_f32_dpp v227, v227, v227 quad_perm:[1,0,3,2] row_mask:0xf bank_mask:0xf bound_ctrl:1
	v_add_f32_dpp v228, v228, v228 quad_perm:[1,0,3,2] row_mask:0xf bank_mask:0xf bound_ctrl:1
	v_add_f32_dpp v229, v229, v229 quad_perm:[1,0,3,2] row_mask:0xf bank_mask:0xf bound_ctrl:1
	v_add_f32_dpp v230, v230, v230 quad_perm:[1,0,3,2] row_mask:0xf bank_mask:0xf bound_ctrl:1
	v_add_f32_dpp v227, v227, v227 quad_perm:[2,3,0,1] row_mask:0xf bank_mask:0xf bound_ctrl:1
	v_add_f32_dpp v228, v228, v228 quad_perm:[2,3,0,1] row_mask:0xf bank_mask:0xf bound_ctrl:1
	v_add_f32_dpp v229, v229, v229 quad_perm:[2,3,0,1] row_mask:0xf bank_mask:0xf bound_ctrl:1
	v_add_f32_dpp v230, v230, v230 quad_perm:[2,3,0,1] row_mask:0xf bank_mask:0xf bound_ctrl:1
	v_add_f32_dpp v227, v227, v227 row_half_mirror row_mask:0xf bank_mask:0xf bound_ctrl:1
	v_add_f32_dpp v228, v228, v228 row_half_mirror row_mask:0xf bank_mask:0xf bound_ctrl:1
	v_add_f32_dpp v229, v229, v229 row_half_mirror row_mask:0xf bank_mask:0xf bound_ctrl:1
	v_add_f32_dpp v230, v230, v230 row_half_mirror row_mask:0xf bank_mask:0xf bound_ctrl:1
	v_add_f32_dpp v227, v227, v227 row_mirror row_mask:0xf bank_mask:0xf bound_ctrl:1
	v_add_f32_dpp v228, v228, v228 row_mirror row_mask:0xf bank_mask:0xf bound_ctrl:1
	v_add_f32_dpp v229, v229, v229 row_mirror row_mask:0xf bank_mask:0xf bound_ctrl:1
	v_add_f32_dpp v230, v230, v230 row_mirror row_mask:0xf bank_mask:0xf bound_ctrl:1
	v_add_f32_dpp v227, v227, v227 row_bcast:15 row_mask:0xa bank_mask:0xf
	v_add_f32_dpp v228, v228, v228 row_bcast:15 row_mask:0xa bank_mask:0xf
	v_add_f32_dpp v229, v229, v229 row_bcast:15 row_mask:0xa bank_mask:0xf
	v_add_f32_dpp v230, v230, v230 row_bcast:15 row_mask:0xa bank_mask:0xf
	v_add_f32_dpp v227, v227, v227 row_bcast:31 row_mask:0xc bank_mask:0xf
	v_add_f32_dpp v228, v228, v228 row_bcast:31 row_mask:0xc bank_mask:0xf
	v_add_f32_dpp v229, v229, v229 row_bcast:31 row_mask:0xc bank_mask:0xf
	v_add_f32_dpp v230, v230, v230 row_bcast:31 row_mask:0xc bank_mask:0xf
	v_readlane_b32 s0, v227, 63
	v_readlane_b32 s1, v228, 63
	v_readlane_b32 s33, v229, 63
	v_readlane_b32 s41, v230, 63
	v_mov_b32_e32 v231, s0
	v_mov_b32_e32 v234, s33
	v_sqrt_f32_e32 v231, v231
	v_mul_f32_e32 v235, s41, v210
	v_max_f32_e32 v231, 0x2b8cbccc, v231
	v_rcp_f32_e32 v231, v231
	v_cvt_pk_bf16_f32 v235, v235, v235
	v_mul_f32_e32 v213, v213, v231
	v_mul_f32_e32 v233, s1, v231
	v_mul_f32_e32 v217, -1.0, v213
	v_rcp_f32_e32 v212, v211
	v_mul_f32_e32 v216, v213, v132
	v_mul_f32_e32 v218, v211, v208
	v_fmac_f32_e32 v218, v233, v217
	ds_write2st64_b32 v222, v217, v218 offset0:0 offset1:1
	v_mul_f32_e32 v219, v216, v212
	v_mul_f32_e32 v220, v215, v212
	ds_write2st64_b32 v222, v211, v219 offset0:2 offset1:3
	ds_write_b32 v222, v220 offset:1024
	ds_write_b32 v223, v210 offset:0
	ds_write_b32 v223, v234 offset:8
	s_bitcmp1_b32 s72, 0
	s_cbranch_scc1 .Lrwq_nobv_0_q
	global_store_short v175, v235, s[6:7]
